# ph0: weight-transpose worker ids rotated by 128 WGs so WGs with 2 adaLN items get fewer transposes
# baseline (speedup 1.0000x reference)
.LBB0_1113:
	s_mov_b32 s0, s56
	s_cmpk_lg_u32 s24, 0x100
	s_cbranch_scc1 .Ltp_nomap
	s_add_u32 s0, s56, 0x80
	s_and_b32 s0, s0, 0xff
.Ltp_nomap:
	s_lshl_b32 s0, s0, 3
	v_readlane_b32 s1, v255, 5
	s_add_i32 s2, s1, s0
	s_lshl_b32 s20, s24, 3
	s_cmpk_gt_i32 s2, 0x12ff
	s_barrier
	s_cbranch_scc1 .LBB0_1125
	s_lshl_b32 s0, s1, 14
	v_and_b32_e32 v0, 7, v192
	s_add_i32 s0, s0, 0
	v_lshlrev_b32_e32 v178, 4, v0
	v_mul_u32_u24_e32 v0, 0x420, v0
	v_lshlrev_b32_e32 v1, 2, v44
	v_add_u32_e32 v12, s0, v178
	v_add3_u32 v17, s0, v0, v1
	v_readlane_b32 s0, v253, 6
	v_readlane_b32 s1, v253, 7
	s_mov_b64 s[60:61], s[84:85]
	v_readlane_b32 s80, v253, 46
	v_lshl_add_u64 v[0:1], s[0:1], 0, v[178:179]
	v_readlane_b32 s0, v254, 18
	v_readlane_b32 s1, v254, 19
	v_readlane_b32 s84, v253, 50
	v_readlane_b32 s85, v253, 51
	v_lshl_add_u64 v[2:3], s[0:1], 0, v[178:179]
	v_readlane_b32 s90, v253, 56
	v_readlane_b32 s91, v253, 57
	s_lshl_b32 s0, s2, 1
	v_mul_u32_u24_e32 v13, 0x84, v44
	v_or_b32_e32 v14, 8, v44
	v_or_b32_e32 v15, 16, v44
	v_or_b32_e32 v16, 24, v44
	v_lshl_add_u64 v[4:5], s[78:79], 0, v[178:179]
	v_lshl_add_u64 v[6:7], s[66:67], 0, v[178:179]
	v_lshl_add_u64 v[8:9], s[90:91], 0, v[178:179]
	v_lshl_add_u64 v[10:11], s[84:85], 0, v[178:179]
	s_lshl_b32 s3, s2, 5
	s_lshl_b32 s21, s20, 5
	s_add_i32 s33, s0, 0x1f400
	s_lshl_b32 s34, s20, 1
	s_mov_b32 s35, s2
	s_mov_b32 s38, 0x10000
	s_movk_i32 s39, 0x3000
	s_mov_b32 s40, 0x2c000
	s_mov_b32 s41, 0x58000
	s_mov_b32 s42, 0x84000
	s_mov_b32 s43, 0xb0000
	s_mov_b32 s56, 0xdc000
	s_mov_b32 s57, 0x108000
	s_mov_b32 s58, 0x134000
	v_readlane_b32 s81, v253, 47
	v_readlane_b32 s82, v253, 48
	v_readlane_b32 s83, v253, 49
	v_readlane_b32 s86, v253, 52
	v_readlane_b32 s87, v253, 53
	v_readlane_b32 s88, v253, 54
	v_readlane_b32 s89, v253, 55
	v_readlane_b32 s92, v253, 58
	v_readlane_b32 s93, v253, 59
	v_readlane_b32 s94, v253, 60
	v_readlane_b32 s95, v253, 61
	s_branch .LBB0_1116
